# DSA phase: waves 4-7 (second wave of each SIMD pair) run at static priority 1
# baseline (speedup 1.0000x reference)
; #define LAS __attribute__((address_space(3)))
; #define LDS_WAIT() asm volatile("s_waitcnt lgkmcnt(0)" ::: "memory")
; __device__ __forceinline__ void dsa_unit(const bf16* QB, const int* SEL, bf16* AO, int b, int kvh, int t, LAS unsigned char* wl, int lane) {
;     ...
;     const int r4 = kq, c16 = l15;
;     const bf16* kg = QB + rowbase * NBP + CK + kvh * 128 + c16 * 8;
;     const bf16* vg = QB + rowbase * NBP + CV + kvh * 128 + c16 * 8;
;     bf16x8 kr[3][8];
; #pragma unroll
;     for (int pb = 0; pb < 3; ++pb)
; #pragma unroll
;         for (int i = 0; i < 8; ++i) kr[pb][i] = *(const bf16x8*)(kg + (size_t)il[32 * pb + 4 * i + r4] * NBP);
;     float lg[8][4];
;     float mx[4] = {-__builtin_inff(), -__builtin_inff(), -__builtin_inff(), -__builtin_inff()};
;     LAS unsigned char* kdst = buf + r4 * 272 + c16 * 16;
;     const LAS unsigned char* kfb = buf + l15 * 272 + 16 * kq;
;     const bool upper = (lane >> 4) & 1;
; __global__ void __launch_bounds__(NWAVES * 64, 2) fwd_megakernel(Args args) {
;     ...
;                 { LAS float* blw = (LAS float*)(wl + 12288);
; #pragma unroll
;                   for (int i = 0; i < 8; ++i) blw[lane + 64 * i] = LOG2E * args.in[I_RELB][lane + 64 * i];
;                   LDS_WAIT(); }
;                 for (int rep = 0; rep < REP_DSA; ++rep)
;                 if ((G & 7) == 0) { const int x = blockIdx.x & 7; const int nxw = (G >> 3) * NWAVES; const int wx = (blockIdx.x >> 3) * NWAVES + wave;
.Ldsa_new:
	v_readfirstlane_b32 s0, v207
	v_readlane_b32 s1, v251, 14
	v_readlane_b32 s12, v251, 0
	v_readlane_b32 s13, v251, 1
	s_lshr_b32 s0, s0, 6
	s_lshr_b32 s2, s84, 3
	s_mov_b32 s16, 0x88000
	s_mov_b32 s17, 0
	s_movk_i32 s23, 0x2200
	v_lshlrev_b32_e32 v178, 2, v207
	s_nop 4
	global_load_dword v179, v178, s[12:13]
	v_and_b32_e32 v64, 31, v206
	v_lshrrev_b32_e32 v65, 5, v206
	v_lshlrev_b32_e32 v175, 3, v65
	v_and_b32_e32 v66, 19, v64
	v_lshrrev_b32_e32 v67, 1, v64
	v_and_b32_e32 v67, 4, v67
	v_lshlrev_b32_e32 v68, 1, v64
	v_and_b32_e32 v68, 8, v68
	v_or3_b32 v66, v66, v67, v68
	v_mul_u32_u24_e32 v66, 0x110, v66
	v_lshl_add_u32 v66, v65, 4, v66
	v_add_u32_e32 v164, 0x4800, v66
	v_bfe_u32 v66, v206, 2, 2
	v_or_b32_e32 v66, v175, v66
	v_mul_u32_u24_e32 v66, 0x120, v66
	v_and_b32_e32 v67, 16, v206
	v_and_b32_e32 v68, 3, v206
	v_lshl_or_b32 v67, v68, 2, v67
	v_lshl_add_u32 v165, v67, 1, v66
	v_lshrrev_b32_e32 v66, 4, v207
	v_and_b32_e32 v67, 15, v207
	v_lshlrev_b32_e32 v67, 4, v67
	v_mul_u32_u24_e32 v68, 0x110, v66
	v_add_u32_e32 v68, v68, v67
	v_add_u32_e32 v166, 0x4800, v68
	v_mul_u32_u24_e32 v68, 0x120, v66
	v_add_u32_e32 v167, v68, v67
	s_waitcnt vmcnt(0)
	v_mul_f32_e32 v179, 0x3fb8aa3b, v179
	v_add_u32_e32 v178, 0x19800, v178
	ds_write_b32 v178, v179
	v_readlane_b32 s46, v251, 19
	v_readlane_b32 s47, v251, 20
	s_mul_i32 s45, s0, 0x2200
	s_add_u32 s24, s45, 0x8c00
	s_add_u32 s25, s45, 0x12c00
	s_cmp_lt_u32 s0, 4
	s_cselect_b32 s45, s24, s25
	s_lshl_b32 s44, s0, 3
	s_waitcnt lgkmcnt(0)
	s_barrier
	s_mov_b32 s3, s1
	s_cmp_lt_u32 s0, 4
	s_cbranch_scc1 .Ldsa_prio_lo
	s_setprio 1
.Ldsa_prio_lo:
.Ldsa_unit:
	s_cmpk_ge_u32 s3, 0x200
	s_cbranch_scc1 .Ldsa_done
	s_and_b32 s24, s3, 7
	s_lshr_b32 s25, s3, 3
	s_and_b32 s35, s25, 31
	s_lshr_b32 s25, s25, 5
	s_lshl_b32 s25, s25, 3
	s_add_u32 s24, s24, s25
	s_lshr_b32 s4, s24, 2
	s_lshl_b32 s4, s4, 12
	s_and_b32 s5, s24, 3
	s_mov_b32 s21, 0

; __global__ void __launch_bounds__(NWAVES * 64, 2) fwd_megakernel(Args args) {
;     ...
;                 __syncthreads();
;             }
;             PH_END
.Ldsa_done:
	s_setprio 0
	s_branch .LBB0_999
